# hand-written out-projection epilogue (packed squares, permlane16/32 swap row sums, one SSQ store per lane)
# baseline (speedup 1.0000x reference)
; #define PG8_STAGE(bufoff, gbase, voff) do { _Pragma("unroll") for (int _i = 0; _i < 2; ++_i) \
;         __builtin_amdgcn_global_load_lds((const __attribute__((address_space(1))) unsigned*)((const char*)(gbase) + (voff)[_i]), (LAS unsigned*)(lds + (bufoff) + ldsw + _i * 8192), 16, 0, 0); } while (0)
; #define PG8_LDA(dst, b, h) do { _Pragma("unroll") for (int m = 0; m < 4; ++m) _Pragma("unroll") for (int k = 0; k < 2; ++k) dst[m][k] = *(const LAS bf16x8*)(lds + PG8_SA(b, h) + aoff + m * 2048 + k * 1024); } while (0)
; #define PG8_LDB(dst, b, h) do { _Pragma("unroll") for (int n = 0; n < 2; ++n) _Pragma("unroll") for (int k = 0; k < 2; ++k) dst[n][k] = *(const LAS bf16x8*)(lds + PG8_SB(b, h) + boff + n * 2048 + k * 1024); } while (0)
; #define PG8_MMA(ai, bj, At, Bt) do { __builtin_amdgcn_s_setprio(1); _Pragma("unroll") for (int m = 0; m < 4; ++m) _Pragma("unroll") for (int n = 0; n < 2; ++n) _Pragma("unroll") for (int k = 0; k < 2; ++k) \
;         acc[ai][bj][m][n] = __builtin_amdgcn_mfma_f32_16x16x32_bf16(Bt[n][k], At[m][k], acc[ai][bj][m][n], 0, 0, 0); __builtin_amdgcn_s_setprio(0); } while (0)
; #define PG8_WAIT_L(n) asm volatile("s_waitcnt lgkmcnt(" #n ")" ::: "memory")
; #define PG8_BAR __builtin_amdgcn_s_barrier()
; #define PG8_SCHED __builtin_amdgcn_sched_barrier(0)
; template <class Epi>
; __device__ __forceinline__ void gemm_phase(LAS unsigned char* lds, const Gemm g, const StaticOrder& S_in, const Epi& E, int sw) {
;     ...
;         for (int t = 0; t < nt; t += 2) {
;             const bool last = (t == nt - 2);
;             const char* a1 = cA + (size_t)(t + 1) * kstep;
;             const char* a2 = last ? nA : cA + (size_t)(t + 2) * kstep; const char* b2 = last ? nB : cB + (size_t)(t + 2) * kstep;
;             const char* a3 = a2 + kstep; const char* b3 = b2 + kstep;
;             PG8_LDB(B0, 0, 0); PG8_SCHED; PG8_LDA(At, 0, 0); PG8_STAGE(PG8_SA(1, 1), a1 + hstepA, voffA);
;             PG8_WAIT_L(8); PG8_BAR; PG8_WAIT_L(0); PG8_MMA(0, 0, At, B0); PG8_BAR; PG8_SCHED;
;             PG8_LDB(B1, 0, 1); PG8_STAGE(PG8_SB(0, 0), b2, voffB);
;             PG8_BAR; PG8_WAIT_L(0); PG8_MMA(0, 1, At, B1); PG8_BAR;
;             PG8_LDA(At, 0, 1); PG8_STAGE(PG8_SA(0, 0), a2, voffA);
;             PG8_BAR; PG8_WAIT_L(0); PG8_MMA(1, 0, At, B0); PG8_BAR; PG8_SCHED;
.LBB0_722:
	s_add_u32 s24, s22, 0xfff80080
	s_addc_u32 s25, s23, -1
	s_add_i32 s53, 0, 0x10000
	v_add_u32_e32 v154, s53, v144
	ds_read_b128 v[140:143], v154
	ds_read_b128 v[146:149], v154 offset:1024
	ds_read_b128 v[150:153], v154 offset:2048
	ds_read_b128 v[154:157], v154 offset:3072
	s_cmp_eq_u32 s52, 28
	s_cselect_b32 s27, s17, s25
	s_cselect_b32 s26, s48, s24
	s_cselect_b32 s25, s13, s51
	s_cselect_b32 s24, s49, s50
	v_lshl_add_u64 v[192:193], s[22:23], 0, v[136:137]
	s_add_i32 m0, s40, 0xc000
	ds_read_b128 v[158:161], v145
	ds_read_b128 v[162:165], v145 offset:1024
	ds_read_b128 v[166:169], v145 offset:2048
	ds_read_b128 v[172:175], v145 offset:3072
	ds_read_b128 v[176:179], v145 offset:4096
	ds_read_b128 v[180:183], v145 offset:5120
	ds_read_b128 v[184:187], v145 offset:6144
	ds_read_b128 v[188:191], v145 offset:7168
	global_load_lds_dwordx4 v[192:193], off
	v_lshl_add_u64 v[192:193], s[22:23], 0, v[138:139]
	s_add_i32 m0, s40, 0xe000
	s_nop 0
	global_load_lds_dwordx4 v[192:193], off
	s_waitcnt lgkmcnt(8)
	s_barrier
	s_waitcnt lgkmcnt(0)
	s_setprio 1
	s_waitcnt lgkmcnt(0)
	v_mfma_f32_16x16x32_bf16 v[126:129], v[140:143], v[158:161], v[126:129]
	v_mfma_f32_16x16x32_bf16 v[122:125], v[150:153], v[158:161], v[122:125]
	v_mfma_f32_16x16x32_bf16 v[110:113], v[140:143], v[166:169], v[110:113]
	v_mfma_f32_16x16x32_bf16 v[106:109], v[150:153], v[166:169], v[106:109]
	v_mfma_f32_16x16x32_bf16 v[94:97], v[140:143], v[176:179], v[94:97]
	v_mfma_f32_16x16x32_bf16 v[90:93], v[150:153], v[176:179], v[90:93]
	v_mfma_f32_16x16x32_bf16 v[78:81], v[140:143], v[184:187], v[78:81]
	v_mfma_f32_16x16x32_bf16 v[74:77], v[150:153], v[184:187], v[74:77]
	v_mfma_f32_16x16x32_bf16 v[126:129], v[146:149], v[162:165], v[126:129]
	v_mfma_f32_16x16x32_bf16 v[122:125], v[154:157], v[162:165], v[122:125]
	v_mfma_f32_16x16x32_bf16 v[110:113], v[146:149], v[172:175], v[110:113]
	v_mfma_f32_16x16x32_bf16 v[106:109], v[154:157], v[172:175], v[106:109]
	v_mfma_f32_16x16x32_bf16 v[94:97], v[146:149], v[180:183], v[94:97]
	v_mfma_f32_16x16x32_bf16 v[90:93], v[154:157], v[180:183], v[90:93]
	v_mfma_f32_16x16x32_bf16 v[78:81], v[146:149], v[188:191], v[78:81]
	v_mfma_f32_16x16x32_bf16 v[74:77], v[154:157], v[188:191], v[74:77]
	s_setprio 0
	s_barrier
	s_add_i32 s56, 0, 0x14000
	s_add_i32 s53, s53, s37
	v_add_u32_e32 v171, s56, v144
	v_lshl_add_u64 v[208:209], s[24:25], 0, v[0:1]
	s_mov_b32 m0, s53
	ds_read_b128 v[192:195], v171
	ds_read_b128 v[196:199], v171 offset:1024
	ds_read_b128 v[200:203], v171 offset:2048
	ds_read_b128 v[204:207], v171 offset:3072
	global_load_lds_dwordx4 v[208:209], off
	v_lshl_add_u64 v[210:211], s[24:25], 0, v[130:131]
	s_add_i32 m0, s53, 0x2000
	s_nop 0
	global_load_lds_dwordx4 v[210:211], off
	s_barrier
	s_waitcnt lgkmcnt(0)
	s_setprio 1
	s_waitcnt lgkmcnt(0)
	v_mfma_f32_16x16x32_bf16 v[118:121], v[192:195], v[158:161], v[118:121]
	v_mfma_f32_16x16x32_bf16 v[114:117], v[200:203], v[158:161], v[114:117]
	v_mfma_f32_16x16x32_bf16 v[102:105], v[192:195], v[166:169], v[102:105]
	v_mfma_f32_16x16x32_bf16 v[98:101], v[200:203], v[166:169], v[98:101]
	v_mfma_f32_16x16x32_bf16 v[86:89], v[192:195], v[176:179], v[86:89]
	v_mfma_f32_16x16x32_bf16 v[82:85], v[200:203], v[176:179], v[82:85]
	v_mfma_f32_16x16x32_bf16 v[70:73], v[192:195], v[184:187], v[70:73]
	v_mfma_f32_16x16x32_bf16 v[66:69], v[200:203], v[184:187], v[66:69]
	v_mfma_f32_16x16x32_bf16 v[118:121], v[196:199], v[162:165], v[118:121]
	v_mfma_f32_16x16x32_bf16 v[114:117], v[204:207], v[162:165], v[114:117]
	v_mfma_f32_16x16x32_bf16 v[102:105], v[196:199], v[172:175], v[102:105]
	v_mfma_f32_16x16x32_bf16 v[98:101], v[204:207], v[172:175], v[98:101]
	v_mfma_f32_16x16x32_bf16 v[86:89], v[196:199], v[180:183], v[86:89]
	v_mfma_f32_16x16x32_bf16 v[82:85], v[204:207], v[180:183], v[82:85]
	v_mfma_f32_16x16x32_bf16 v[70:73], v[196:199], v[188:191], v[70:73]
	v_mfma_f32_16x16x32_bf16 v[66:69], v[204:207], v[188:191], v[66:69]
	s_setprio 0
	s_mov_b32 m0, s40
	v_lshl_add_u64 v[212:213], s[26:27], 0, v[134:135]
	s_barrier
	ds_read_b128 v[158:161], v145 offset:16384
	ds_read_b128 v[162:165], v145 offset:17408
	ds_read_b128 v[166:169], v145 offset:18432
	ds_read_b128 v[172:175], v145 offset:19456
	ds_read_b128 v[176:179], v145 offset:20480
	ds_read_b128 v[180:183], v145 offset:21504
	ds_read_b128 v[184:187], v145 offset:22528
	ds_read_b128 v[188:191], v145 offset:23552
	global_load_lds_dwordx4 v[212:213], off
	v_lshl_add_u64 v[214:215], s[26:27], 0, v[132:133]
	s_mov_b32 m0, s41
	s_nop 0
	global_load_lds_dwordx4 v[214:215], off
	s_barrier
	s_waitcnt lgkmcnt(0)
	s_setprio 1
	s_waitcnt lgkmcnt(0)
	v_mfma_f32_16x16x32_bf16 v[62:65], v[140:143], v[158:161], v[62:65]
	v_mfma_f32_16x16x32_bf16 v[58:61], v[150:153], v[158:161], v[58:61]
	v_mfma_f32_16x16x32_bf16 v[46:49], v[140:143], v[166:169], v[46:49]
	v_mfma_f32_16x16x32_bf16 v[42:45], v[150:153], v[166:169], v[42:45]
	v_mfma_f32_16x16x32_bf16 v[30:33], v[140:143], v[176:179], v[30:33]
	v_mfma_f32_16x16x32_bf16 v[26:29], v[150:153], v[176:179], v[26:29]
	v_mfma_f32_16x16x32_bf16 v[14:17], v[140:143], v[184:187], v[14:17]
	v_mfma_f32_16x16x32_bf16 v[10:13], v[150:153], v[184:187], v[10:13]
	v_mfma_f32_16x16x32_bf16 v[62:65], v[146:149], v[162:165], v[62:65]
	v_mfma_f32_16x16x32_bf16 v[58:61], v[154:157], v[162:165], v[58:61]
	v_mfma_f32_16x16x32_bf16 v[46:49], v[146:149], v[172:175], v[46:49]
	v_mfma_f32_16x16x32_bf16 v[42:45], v[154:157], v[172:175], v[42:45]
	v_mfma_f32_16x16x32_bf16 v[30:33], v[146:149], v[180:183], v[30:33]
	v_mfma_f32_16x16x32_bf16 v[26:29], v[154:157], v[180:183], v[26:29]
	v_mfma_f32_16x16x32_bf16 v[14:17], v[146:149], v[188:191], v[14:17]
	v_mfma_f32_16x16x32_bf16 v[10:13], v[154:157], v[188:191], v[10:13]
	s_setprio 0
	s_barrier
; #define PG8_STAGE(bufoff, gbase, voff) do { _Pragma("unroll") for (int _i = 0; _i < 2; ++_i) \
;         __builtin_amdgcn_global_load_lds((const __attribute__((address_space(1))) unsigned*)((const char*)(gbase) + (voff)[_i]), (LAS unsigned*)(lds + (bufoff) + ldsw + _i * 8192), 16, 0, 0); } while (0)
; #define PG8_LDA(dst, b, h) do { _Pragma("unroll") for (int m = 0; m < 4; ++m) _Pragma("unroll") for (int k = 0; k < 2; ++k) dst[m][k] = *(const LAS bf16x8*)(lds + PG8_SA(b, h) + aoff + m * 2048 + k * 1024); } while (0)
; #define PG8_LDB(dst, b, h) do { _Pragma("unroll") for (int n = 0; n < 2; ++n) _Pragma("unroll") for (int k = 0; k < 2; ++k) dst[n][k] = *(const LAS bf16x8*)(lds + PG8_SB(b, h) + boff + n * 2048 + k * 1024); } while (0)
; #define PG8_MMA(ai, bj, At, Bt) do { __builtin_amdgcn_s_setprio(1); _Pragma("unroll") for (int m = 0; m < 4; ++m) _Pragma("unroll") for (int n = 0; n < 2; ++n) _Pragma("unroll") for (int k = 0; k < 2; ++k) \
;         acc[ai][bj][m][n] = __builtin_amdgcn_mfma_f32_16x16x32_bf16(Bt[n][k], At[m][k], acc[ai][bj][m][n], 0, 0, 0); __builtin_amdgcn_s_setprio(0); } while (0)
; #define PG8_WAIT_V(n) asm volatile("s_waitcnt vmcnt(" #n ")" ::: "memory")
; #define PG8_WAIT_L(n) asm volatile("s_waitcnt lgkmcnt(" #n ")" ::: "memory")
; #define PG8_BAR __builtin_amdgcn_s_barrier()
; #define PG8_SCHED __builtin_amdgcn_sched_barrier(0)
; template <class Epi>
; __device__ __forceinline__ void gemm_phase(LAS unsigned char* lds, const Gemm g, const StaticOrder& S_in, const Epi& E, int sw) {
;     ...
;             PG8_STAGE(PG8_SB(0, 1), b2 + hstepB, voffB);
;             PG8_WAIT_V(6); PG8_BAR; PG8_MMA(1, 1, At, B1); PG8_BAR;
;             PG8_LDB(B0, 1, 0); PG8_SCHED; PG8_LDA(At, 1, 0); PG8_STAGE(PG8_SA(0, 1), a2 + hstepA, voffA);
;             PG8_WAIT_L(8); PG8_BAR; PG8_WAIT_L(0); PG8_MMA(0, 0, At, B0); PG8_BAR; PG8_SCHED;
;             PG8_LDB(B1, 1, 1); PG8_STAGE(PG8_SB(1, 0), b3, voffB);
;             PG8_BAR; PG8_WAIT_L(0); PG8_MMA(0, 1, At, B1); PG8_BAR;
;             PG8_LDA(At, 1, 1); PG8_STAGE(PG8_SA(1, 0), a3, voffA);
;             PG8_BAR; PG8_WAIT_L(0); PG8_MMA(1, 0, At, B0); PG8_BAR; PG8_SCHED;
	s_add_u32 s54, s24, 0x80000
	s_addc_u32 s55, s25, 0
	s_add_i32 s53, s56, s37
	v_lshl_add_u64 v[140:141], s[54:55], 0, v[0:1]
	s_mov_b32 m0, s53
	s_nop 0
	global_load_lds_dwordx4 v[140:141], off
	v_lshl_add_u64 v[140:141], s[54:55], 0, v[130:131]
	s_add_i32 m0, s53, 0x2000
	s_nop 0
	global_load_lds_dwordx4 v[140:141], off
	s_waitcnt vmcnt(6)
	s_barrier
	s_setprio 1
	v_mfma_f32_16x16x32_bf16 v[54:57], v[192:195], v[158:161], v[54:57]
	v_mfma_f32_16x16x32_bf16 v[50:53], v[200:203], v[158:161], v[50:53]
	v_mfma_f32_16x16x32_bf16 v[38:41], v[192:195], v[166:169], v[38:41]
	v_mfma_f32_16x16x32_bf16 v[34:37], v[200:203], v[166:169], v[34:37]
	v_mfma_f32_16x16x32_bf16 v[22:25], v[192:195], v[176:179], v[22:25]
	v_mfma_f32_16x16x32_bf16 v[18:21], v[200:203], v[176:179], v[18:21]
	v_mfma_f32_16x16x32_bf16 v[6:9], v[192:195], v[184:187], v[6:9]
	v_mfma_f32_16x16x32_bf16 v[2:5], v[200:203], v[184:187], v[2:5]
	v_mfma_f32_16x16x32_bf16 v[54:57], v[196:199], v[162:165], v[54:57]
	v_mfma_f32_16x16x32_bf16 v[50:53], v[204:207], v[162:165], v[50:53]
	v_mfma_f32_16x16x32_bf16 v[38:41], v[196:199], v[172:175], v[38:41]
	v_mfma_f32_16x16x32_bf16 v[34:37], v[204:207], v[172:175], v[34:37]
	v_mfma_f32_16x16x32_bf16 v[22:25], v[196:199], v[180:183], v[22:25]
	v_mfma_f32_16x16x32_bf16 v[18:21], v[204:207], v[180:183], v[18:21]
	v_mfma_f32_16x16x32_bf16 v[6:9], v[196:199], v[188:191], v[6:9]
	v_mfma_f32_16x16x32_bf16 v[2:5], v[204:207], v[188:191], v[2:5]
	s_setprio 0
	s_add_i32 s53, 0, 0x18000
	v_add_u32_e32 v154, s53, v144
	s_barrier
	ds_read_b128 v[140:143], v154
	ds_read_b128 v[146:149], v154 offset:1024
	ds_read_b128 v[150:153], v154 offset:2048
	ds_read_b128 v[154:157], v154 offset:3072
	s_add_u32 s26, s26, 0x80000
	s_addc_u32 s27, s27, 0
	s_mov_b32 m0, s42
	v_lshl_add_u64 v[192:193], s[26:27], 0, v[134:135]
	ds_read_b128 v[158:161], v145 offset:32768
	ds_read_b128 v[162:165], v145 offset:33792
	ds_read_b128 v[166:169], v145 offset:34816
	ds_read_b128 v[172:175], v145 offset:35840
	ds_read_b128 v[176:179], v145 offset:36864
	ds_read_b128 v[180:183], v145 offset:37888
	ds_read_b128 v[184:187], v145 offset:38912
	ds_read_b128 v[188:191], v145 offset:39936
	global_load_lds_dwordx4 v[192:193], off
	v_lshl_add_u64 v[192:193], s[26:27], 0, v[132:133]
	s_mov_b32 m0, s43
	s_nop 0
	global_load_lds_dwordx4 v[192:193], off
	s_waitcnt lgkmcnt(8)
	s_barrier
	s_waitcnt lgkmcnt(0)
	s_setprio 1
	s_waitcnt lgkmcnt(0)
	v_mfma_f32_16x16x32_bf16 v[126:129], v[140:143], v[158:161], v[126:129]
	v_mfma_f32_16x16x32_bf16 v[122:125], v[150:153], v[158:161], v[122:125]
	v_mfma_f32_16x16x32_bf16 v[110:113], v[140:143], v[166:169], v[110:113]
	v_mfma_f32_16x16x32_bf16 v[106:109], v[150:153], v[166:169], v[106:109]
	v_mfma_f32_16x16x32_bf16 v[94:97], v[140:143], v[176:179], v[94:97]
	v_mfma_f32_16x16x32_bf16 v[90:93], v[150:153], v[176:179], v[90:93]
	v_mfma_f32_16x16x32_bf16 v[78:81], v[140:143], v[184:187], v[78:81]
	v_mfma_f32_16x16x32_bf16 v[74:77], v[150:153], v[184:187], v[74:77]
	v_mfma_f32_16x16x32_bf16 v[126:129], v[146:149], v[162:165], v[126:129]
	v_mfma_f32_16x16x32_bf16 v[122:125], v[154:157], v[162:165], v[122:125]
	v_mfma_f32_16x16x32_bf16 v[110:113], v[146:149], v[172:175], v[110:113]
	v_mfma_f32_16x16x32_bf16 v[106:109], v[154:157], v[172:175], v[106:109]
	v_mfma_f32_16x16x32_bf16 v[94:97], v[146:149], v[180:183], v[94:97]
	v_mfma_f32_16x16x32_bf16 v[90:93], v[154:157], v[180:183], v[90:93]
	v_mfma_f32_16x16x32_bf16 v[78:81], v[146:149], v[188:191], v[78:81]
	v_mfma_f32_16x16x32_bf16 v[74:77], v[154:157], v[188:191], v[74:77]
	s_setprio 0
	s_barrier
	s_add_i32 s26, 0, 0x1c000
	s_add_i32 s27, s53, s37
	v_add_u32_e32 v171, s26, v144
	v_lshl_add_u64 v[208:209], v[208:209], 0, s[86:87]
	s_mov_b32 m0, s27
	ds_read_b128 v[192:195], v171
	ds_read_b128 v[196:199], v171 offset:1024
	ds_read_b128 v[200:203], v171 offset:2048
	ds_read_b128 v[204:207], v171 offset:3072
	global_load_lds_dwordx4 v[208:209], off
	v_lshl_add_u64 v[208:209], v[210:211], 0, s[86:87]
	s_add_i32 m0, s27, 0x2000
	s_nop 0
	global_load_lds_dwordx4 v[208:209], off
	s_barrier
	s_waitcnt lgkmcnt(0)
	s_setprio 1
	s_waitcnt lgkmcnt(0)
	v_mfma_f32_16x16x32_bf16 v[118:121], v[192:195], v[158:161], v[118:121]
	v_mfma_f32_16x16x32_bf16 v[114:117], v[200:203], v[158:161], v[114:117]
	v_mfma_f32_16x16x32_bf16 v[102:105], v[192:195], v[166:169], v[102:105]
	v_mfma_f32_16x16x32_bf16 v[98:101], v[200:203], v[166:169], v[98:101]
	v_mfma_f32_16x16x32_bf16 v[86:89], v[192:195], v[176:179], v[86:89]
	v_mfma_f32_16x16x32_bf16 v[82:85], v[200:203], v[176:179], v[82:85]
	v_mfma_f32_16x16x32_bf16 v[70:73], v[192:195], v[184:187], v[70:73]
	v_mfma_f32_16x16x32_bf16 v[66:69], v[200:203], v[184:187], v[66:69]
	v_mfma_f32_16x16x32_bf16 v[118:121], v[196:199], v[162:165], v[118:121]
	v_mfma_f32_16x16x32_bf16 v[114:117], v[204:207], v[162:165], v[114:117]
	v_mfma_f32_16x16x32_bf16 v[102:105], v[196:199], v[172:175], v[102:105]
	v_mfma_f32_16x16x32_bf16 v[98:101], v[204:207], v[172:175], v[98:101]
	v_mfma_f32_16x16x32_bf16 v[86:89], v[196:199], v[180:183], v[86:89]
	v_mfma_f32_16x16x32_bf16 v[82:85], v[204:207], v[180:183], v[82:85]
	v_mfma_f32_16x16x32_bf16 v[70:73], v[196:199], v[188:191], v[70:73]
	v_mfma_f32_16x16x32_bf16 v[66:69], v[204:207], v[188:191], v[66:69]
	s_setprio 0
	s_mov_b32 m0, s44
	v_lshl_add_u64 v[208:209], v[212:213], 0, s[86:87]
	s_barrier
	ds_read_b128 v[158:161], v145 offset:49152
	ds_read_b128 v[162:165], v145 offset:50176
	ds_read_b128 v[166:169], v145 offset:51200
	ds_read_b128 v[172:175], v145 offset:52224
	ds_read_b128 v[176:179], v145 offset:53248
	ds_read_b128 v[180:183], v145 offset:54272
	ds_read_b128 v[184:187], v145 offset:55296
	ds_read_b128 v[188:191], v145 offset:56320
	global_load_lds_dwordx4 v[208:209], off
	v_lshl_add_u64 v[208:209], v[214:215], 0, s[86:87]
	s_mov_b32 m0, s45
	s_nop 0
	global_load_lds_dwordx4 v[208:209], off
	s_barrier
; __device__ __forceinline__ unsigned cvt_pk_bf16(float lo, float hi) { unsigned r; asm volatile("v_cvt_pk_bf16_f32 %0, %1, %2" : "=v"(r) : "v"(lo), "v"(hi)); return r; }
; __device__ __forceinline__ int ltid(int sw) { unsigned z = 0u; asm volatile("" : "+s"(sw), "+s"(z)); int t = sw * 64 + (int)__builtin_amdgcn_mbcnt_hi(~0u, __builtin_amdgcn_mbcnt_lo(~0u, z)); asm volatile("" : "+v"(t)); return t; }
; #define PG8_STAGE(bufoff, gbase, voff) do { _Pragma("unroll") for (int _i = 0; _i < 2; ++_i) \
;         __builtin_amdgcn_global_load_lds((const __attribute__((address_space(1))) unsigned*)((const char*)(gbase) + (voff)[_i]), (LAS unsigned*)(lds + (bufoff) + ldsw + _i * 8192), 16, 0, 0); } while (0)
; #define PG8_WAIT_V(n) asm volatile("s_waitcnt vmcnt(" #n ")" ::: "memory")
; #define PG8_BAR __builtin_amdgcn_s_barrier()
; template <class Epi>
; __device__ __forceinline__ void gemm_phase(LAS unsigned char* lds, const Gemm g, const StaticOrder& S_in, const Epi& E, int sw) {
;     ...
;             PG8_BAR; PG8_WAIT_L(0); PG8_MMA(1, 0, At, B0); PG8_BAR; PG8_SCHED;
;             PG8_STAGE(PG8_SB(1, 1), b3 + hstepB, voffB);
;             PG8_WAIT_V(6); PG8_BAR; PG8_MMA(1, 1, At, B1); PG8_BAR;
;         }
;     EPI_ZERO_INIT
;     __device__ __forceinline__ void operator()(AccRef acc, const Unit& u, int sw) const {
;         const int tid_ = ltid(sw), lane_ = tid_ & 63, wr = sw >> 2, wc = sw & 3, fr = lane_ & 15, fq = lane_ >> 4;
;         const int row0 = u.pm * BM + wr * 64 + fr, col0 = u.pn * BM + wc * 32 + 8 * fq;
; #pragma unroll
;         for (int ai = 0; ai < 2; ++ai)
; #pragma unroll
;             for (int m = 0; m < 4; ++m) { const int row = row0 + ai * HALF + m * 16; bf16_t* rowp = O + (size_t)row * D + col0; float s = 0.f;
; #pragma unroll
;                 for (int bj = 0; bj < 2; ++bj) { const f32x4 v0 = acc[ai][bj][m][0], v1 = acc[ai][bj][m][1];
;                     s += (v0[0] * v0[0] + v0[1] * v0[1]) + (v0[2] * v0[2] + v0[3] * v0[3]) + (v1[0] * v1[0] + v1[1] * v1[1]) + (v1[2] * v1[2] + v1[3] * v1[3]);
;                     u32x4 w; w.x = cvt_pk_bf16(v0[0], v0[1]); w.y = cvt_pk_bf16(v0[2], v0[3]); w.z = cvt_pk_bf16(v1[0], v1[1]); w.w = cvt_pk_bf16(v1[2], v1[3]);
;                     *(u32x4*)(rowp + bj * HALF) = w; }
;                 s += __shfl_xor(s, 16); s += __shfl_xor(s, 32);
;                 if (fq == 0) SSQ[(size_t)row * 16 + u.pn * 4 + wc] = s; }
	s_waitcnt lgkmcnt(0)
	s_setprio 1
	s_waitcnt lgkmcnt(0)
	v_mfma_f32_16x16x32_bf16 v[62:65], v[140:143], v[158:161], v[62:65]
	v_mfma_f32_16x16x32_bf16 v[58:61], v[150:153], v[158:161], v[58:61]
	v_mfma_f32_16x16x32_bf16 v[46:49], v[140:143], v[166:169], v[46:49]
	v_mfma_f32_16x16x32_bf16 v[42:45], v[150:153], v[166:169], v[42:45]
	v_mfma_f32_16x16x32_bf16 v[30:33], v[140:143], v[176:179], v[30:33]
	v_mfma_f32_16x16x32_bf16 v[26:29], v[150:153], v[176:179], v[26:29]
	v_mfma_f32_16x16x32_bf16 v[14:17], v[140:143], v[184:187], v[14:17]
	v_mfma_f32_16x16x32_bf16 v[10:13], v[150:153], v[184:187], v[10:13]
	v_mfma_f32_16x16x32_bf16 v[62:65], v[146:149], v[162:165], v[62:65]
	v_mfma_f32_16x16x32_bf16 v[58:61], v[154:157], v[162:165], v[58:61]
	v_mfma_f32_16x16x32_bf16 v[46:49], v[146:149], v[172:175], v[46:49]
	v_mfma_f32_16x16x32_bf16 v[42:45], v[154:157], v[172:175], v[42:45]
	v_mfma_f32_16x16x32_bf16 v[30:33], v[146:149], v[180:183], v[30:33]
	v_mfma_f32_16x16x32_bf16 v[26:29], v[154:157], v[180:183], v[26:29]
	v_mfma_f32_16x16x32_bf16 v[14:17], v[146:149], v[188:191], v[14:17]
	v_mfma_f32_16x16x32_bf16 v[10:13], v[154:157], v[188:191], v[10:13]
	s_setprio 0
	s_barrier
	s_add_u32 s24, s24, 0x80080
	s_addc_u32 s25, s25, 0
	s_add_i32 s26, s26, s37
	v_lshl_add_u64 v[140:141], s[24:25], 0, v[0:1]
	s_mov_b32 m0, s26
	s_nop 0
	global_load_lds_dwordx4 v[140:141], off
	v_lshl_add_u64 v[140:141], s[24:25], 0, v[130:131]
	s_add_i32 m0, s26, 0x2000
	s_nop 0
	global_load_lds_dwordx4 v[140:141], off
	s_waitcnt vmcnt(6)
	s_barrier
	s_setprio 1
	v_mfma_f32_16x16x32_bf16 v[54:57], v[192:195], v[158:161], v[54:57]
	v_mfma_f32_16x16x32_bf16 v[50:53], v[200:203], v[158:161], v[50:53]
	v_mfma_f32_16x16x32_bf16 v[38:41], v[192:195], v[166:169], v[38:41]
	v_mfma_f32_16x16x32_bf16 v[34:37], v[200:203], v[166:169], v[34:37]
	v_mfma_f32_16x16x32_bf16 v[22:25], v[192:195], v[176:179], v[22:25]
	v_mfma_f32_16x16x32_bf16 v[18:21], v[200:203], v[176:179], v[18:21]
	v_mfma_f32_16x16x32_bf16 v[6:9], v[192:195], v[184:187], v[6:9]
	v_mfma_f32_16x16x32_bf16 v[2:5], v[200:203], v[184:187], v[2:5]
	v_mfma_f32_16x16x32_bf16 v[54:57], v[196:199], v[162:165], v[54:57]
	v_mfma_f32_16x16x32_bf16 v[50:53], v[204:207], v[162:165], v[50:53]
	v_mfma_f32_16x16x32_bf16 v[38:41], v[196:199], v[172:175], v[38:41]
	v_mfma_f32_16x16x32_bf16 v[34:37], v[204:207], v[172:175], v[34:37]
	v_mfma_f32_16x16x32_bf16 v[22:25], v[196:199], v[180:183], v[22:25]
	v_mfma_f32_16x16x32_bf16 v[18:21], v[204:207], v[180:183], v[18:21]
	v_mfma_f32_16x16x32_bf16 v[6:9], v[196:199], v[188:191], v[6:9]
	v_mfma_f32_16x16x32_bf16 v[2:5], v[204:207], v[188:191], v[2:5]
	s_setprio 0
	s_add_i32 s52, s52, 2
	s_add_u32 s22, s22, 0x100
	s_addc_u32 s23, s23, 0
	s_add_u32 s50, s50, 0x100
	s_addc_u32 s51, s51, 0
	s_cmp_gt_u32 s52, 29
	s_barrier
	s_cbranch_scc0 .LBB0_722
	v_mbcnt_lo_u32_b32 v140, -1, 0
	v_mbcnt_hi_u32_b32 v140, -1, v140
	s_lshl_b32 s6, s6, 8
	s_add_i32 s6, s6, s3
	v_readlane_b32 s13, v255, 5
	v_and_b32_e32 v141, 15, v140
	v_lshrrev_b32_e32 v142, 4, v140
	v_or_b32_e32 v141, s6, v141
	v_lshl_add_u32 v151, v142, 4, v141
	v_lshlrev_b32_e32 v142, 3, v142
	s_lshl_b32 s6, s7, 8
	s_or_b32 s6, s6, s13
	v_readlane_b32 s13, v255, 4
	v_or_b32_e32 v142, s6, v142
	v_lshlrev_b32_e32 v143, 11, v141
	v_lshl_add_u32 v143, v142, 1, v143
	s_lshl_b32 s7, s7, 2
	s_add_i32 s7, s7, s13
	s_lshl_b32 s7, s7, 2
	v_lshlrev_b32_e32 v151, 6, v151
	v_add_u32_e32 v151, s7, v151
	v_add_u32_e32 v156, 0x2000, v151
	v_pk_mul_f32 v[152:153], v[126:127], v[126:127]
	v_pk_mul_f32 v[154:155], v[118:119], v[118:119]
	v_pk_fma_f32 v[152:153], v[128:129], v[128:129], v[152:153]
	v_pk_fma_f32 v[154:155], v[120:121], v[120:121], v[154:155]
	v_pk_fma_f32 v[152:153], v[122:123], v[122:123], v[152:153]
	v_pk_fma_f32 v[154:155], v[114:115], v[114:115], v[154:155]
	v_pk_fma_f32 v[152:153], v[124:125], v[124:125], v[152:153]
	v_pk_fma_f32 v[154:155], v[116:117], v[116:117], v[154:155]
	v_cvt_pk_bf16_f32 v146, v126, v127
	v_cvt_pk_bf16_f32 v147, v128, v129
	v_cvt_pk_bf16_f32 v148, v122, v123
	v_cvt_pk_bf16_f32 v149, v124, v125
	global_store_dwordx4 v143, v[146:149], s[8:9]
	v_pk_add_f32 v[152:153], v[152:153], v[154:155]
	v_cvt_pk_bf16_f32 v168, v118, v119
	v_cvt_pk_bf16_f32 v169, v120, v121
	v_cvt_pk_bf16_f32 v170, v114, v115
	v_cvt_pk_bf16_f32 v171, v116, v117
	global_store_dwordx4 v143, v[168:171], s[8:9] offset:256
	v_add_f32_e32 v160, v152, v153
	v_pk_mul_f32 v[152:153], v[110:111], v[110:111]
	v_pk_mul_f32 v[154:155], v[102:103], v[102:103]
	v_pk_fma_f32 v[152:153], v[112:113], v[112:113], v[152:153]
	v_pk_fma_f32 v[154:155], v[104:105], v[104:105], v[154:155]
	v_pk_fma_f32 v[152:153], v[106:107], v[106:107], v[152:153]
	v_pk_fma_f32 v[154:155], v[98:99], v[98:99], v[154:155]
	v_pk_fma_f32 v[152:153], v[108:109], v[108:109], v[152:153]
	v_pk_fma_f32 v[154:155], v[100:101], v[100:101], v[154:155]
	v_add_u32_e32 v150, 0x8000, v143
	v_cvt_pk_bf16_f32 v146, v110, v111
	v_cvt_pk_bf16_f32 v147, v112, v113
	v_cvt_pk_bf16_f32 v148, v106, v107
	v_cvt_pk_bf16_f32 v149, v108, v109
	global_store_dwordx4 v150, v[146:149], s[8:9]
	v_pk_add_f32 v[152:153], v[152:153], v[154:155]
	v_cvt_pk_bf16_f32 v168, v102, v103
	v_cvt_pk_bf16_f32 v169, v104, v105
	v_cvt_pk_bf16_f32 v170, v98, v99
	v_cvt_pk_bf16_f32 v171, v100, v101
	global_store_dwordx4 v150, v[168:171], s[8:9] offset:256
	v_add_f32_e32 v161, v152, v153
	v_pk_mul_f32 v[152:153], v[94:95], v[94:95]
	v_pk_mul_f32 v[154:155], v[86:87], v[86:87]
	v_pk_fma_f32 v[152:153], v[96:97], v[96:97], v[152:153]
	v_pk_fma_f32 v[154:155], v[88:89], v[88:89], v[154:155]
	v_pk_fma_f32 v[152:153], v[90:91], v[90:91], v[152:153]
; __device__ __forceinline__ unsigned cvt_pk_bf16(float lo, float hi) { unsigned r; asm volatile("v_cvt_pk_bf16_f32 %0, %1, %2" : "=v"(r) : "v"(lo), "v"(hi)); return r; }
;     EPI_ZERO_INIT
;     __device__ __forceinline__ void operator()(AccRef acc, const Unit& u, int sw) const {
;     ...
;             for (int m = 0; m < 4; ++m) { const int row = row0 + ai * HALF + m * 16; bf16_t* rowp = O + (size_t)row * D + col0; float s = 0.f;
; #pragma unroll
;                 for (int bj = 0; bj < 2; ++bj) { const f32x4 v0 = acc[ai][bj][m][0], v1 = acc[ai][bj][m][1];
;                     s += (v0[0] * v0[0] + v0[1] * v0[1]) + (v0[2] * v0[2] + v0[3] * v0[3]) + (v1[0] * v1[0] + v1[1] * v1[1]) + (v1[2] * v1[2] + v1[3] * v1[3]);
;                     u32x4 w; w.x = cvt_pk_bf16(v0[0], v0[1]); w.y = cvt_pk_bf16(v0[2], v0[3]); w.z = cvt_pk_bf16(v1[0], v1[1]); w.w = cvt_pk_bf16(v1[2], v1[3]);
;                     *(u32x4*)(rowp + bj * HALF) = w; }
;                 s += __shfl_xor(s, 16); s += __shfl_xor(s, 32);
;                 if (fq == 0) SSQ[(size_t)row * 16 + u.pn * 4 + wc] = s; }
	v_pk_fma_f32 v[154:155], v[82:83], v[82:83], v[154:155]
	v_pk_fma_f32 v[152:153], v[92:93], v[92:93], v[152:153]
	v_pk_fma_f32 v[154:155], v[84:85], v[84:85], v[154:155]
	v_add_u32_e32 v150, 0x10000, v143
	v_cvt_pk_bf16_f32 v146, v94, v95
	v_cvt_pk_bf16_f32 v147, v96, v97
	v_cvt_pk_bf16_f32 v148, v90, v91
	v_cvt_pk_bf16_f32 v149, v92, v93
	global_store_dwordx4 v150, v[146:149], s[8:9]
	v_pk_add_f32 v[152:153], v[152:153], v[154:155]
	v_cvt_pk_bf16_f32 v168, v86, v87
	v_cvt_pk_bf16_f32 v169, v88, v89
	v_cvt_pk_bf16_f32 v170, v82, v83
	v_cvt_pk_bf16_f32 v171, v84, v85
	global_store_dwordx4 v150, v[168:171], s[8:9] offset:256
	v_add_f32_e32 v162, v152, v153
	v_pk_mul_f32 v[152:153], v[78:79], v[78:79]
	v_pk_mul_f32 v[154:155], v[70:71], v[70:71]
	v_pk_fma_f32 v[152:153], v[80:81], v[80:81], v[152:153]
	v_pk_fma_f32 v[154:155], v[72:73], v[72:73], v[154:155]
	v_pk_fma_f32 v[152:153], v[74:75], v[74:75], v[152:153]
	v_pk_fma_f32 v[154:155], v[66:67], v[66:67], v[154:155]
	v_pk_fma_f32 v[152:153], v[76:77], v[76:77], v[152:153]
	v_pk_fma_f32 v[154:155], v[68:69], v[68:69], v[154:155]
	v_add_u32_e32 v150, 0x18000, v143
	v_cvt_pk_bf16_f32 v146, v78, v79
	v_cvt_pk_bf16_f32 v147, v80, v81
	v_cvt_pk_bf16_f32 v148, v74, v75
	v_cvt_pk_bf16_f32 v149, v76, v77
	global_store_dwordx4 v150, v[146:149], s[8:9]
	v_pk_add_f32 v[152:153], v[152:153], v[154:155]
	v_cvt_pk_bf16_f32 v168, v70, v71
	v_cvt_pk_bf16_f32 v169, v72, v73
	v_cvt_pk_bf16_f32 v170, v66, v67
	v_cvt_pk_bf16_f32 v171, v68, v69
	global_store_dwordx4 v150, v[168:171], s[8:9] offset:256
	v_add_f32_e32 v163, v152, v153
	s_nop 1
	v_permlane16_swap_b32_e32 v160, v161
	v_permlane16_swap_b32_e32 v162, v163
	s_nop 1
	v_add_f32_e32 v160, v160, v161
	v_add_f32_e32 v162, v162, v163
	s_nop 1
	v_permlane32_swap_b32_e32 v160, v162
	s_nop 1
	v_add_f32_e32 v160, v160, v162
	global_store_dword v151, v160, s[10:11]
	v_pk_mul_f32 v[152:153], v[62:63], v[62:63]
	v_pk_mul_f32 v[154:155], v[54:55], v[54:55]
	v_pk_fma_f32 v[152:153], v[64:65], v[64:65], v[152:153]
	v_pk_fma_f32 v[154:155], v[56:57], v[56:57], v[154:155]
	v_pk_fma_f32 v[152:153], v[58:59], v[58:59], v[152:153]
	v_pk_fma_f32 v[154:155], v[50:51], v[50:51], v[154:155]
	v_pk_fma_f32 v[152:153], v[60:61], v[60:61], v[152:153]
	v_pk_fma_f32 v[154:155], v[52:53], v[52:53], v[154:155]
	v_add_u32_e32 v150, 0x40000, v143
	v_cvt_pk_bf16_f32 v146, v62, v63
	v_cvt_pk_bf16_f32 v147, v64, v65
	v_cvt_pk_bf16_f32 v148, v58, v59
	v_cvt_pk_bf16_f32 v149, v60, v61
	global_store_dwordx4 v150, v[146:149], s[8:9]
	v_pk_add_f32 v[152:153], v[152:153], v[154:155]
	v_cvt_pk_bf16_f32 v168, v54, v55
	v_cvt_pk_bf16_f32 v169, v56, v57
	v_cvt_pk_bf16_f32 v170, v50, v51
	v_cvt_pk_bf16_f32 v171, v52, v53
	global_store_dwordx4 v150, v[168:171], s[8:9] offset:256
	v_add_f32_e32 v164, v152, v153
	v_pk_mul_f32 v[152:153], v[46:47], v[46:47]
	v_pk_mul_f32 v[154:155], v[38:39], v[38:39]
	v_pk_fma_f32 v[152:153], v[48:49], v[48:49], v[152:153]
	v_pk_fma_f32 v[154:155], v[40:41], v[40:41], v[154:155]
	v_pk_fma_f32 v[152:153], v[42:43], v[42:43], v[152:153]
	v_pk_fma_f32 v[154:155], v[34:35], v[34:35], v[154:155]
	v_pk_fma_f32 v[152:153], v[44:45], v[44:45], v[152:153]
	v_pk_fma_f32 v[154:155], v[36:37], v[36:37], v[154:155]
	v_add_u32_e32 v150, 0x48000, v143
	v_cvt_pk_bf16_f32 v146, v46, v47
	v_cvt_pk_bf16_f32 v147, v48, v49
	v_cvt_pk_bf16_f32 v148, v42, v43
	v_cvt_pk_bf16_f32 v149, v44, v45
	global_store_dwordx4 v150, v[146:149], s[8:9]
	v_pk_add_f32 v[152:153], v[152:153], v[154:155]
	v_cvt_pk_bf16_f32 v168, v38, v39
	v_cvt_pk_bf16_f32 v169, v40, v41
	v_cvt_pk_bf16_f32 v170, v34, v35
	v_cvt_pk_bf16_f32 v171, v36, v37
	global_store_dwordx4 v150, v[168:171], s[8:9] offset:256
	v_add_f32_e32 v165, v152, v153
	v_pk_mul_f32 v[152:153], v[30:31], v[30:31]
	v_pk_mul_f32 v[154:155], v[22:23], v[22:23]
	v_pk_fma_f32 v[152:153], v[32:33], v[32:33], v[152:153]
	v_pk_fma_f32 v[154:155], v[24:25], v[24:25], v[154:155]
	v_pk_fma_f32 v[152:153], v[26:27], v[26:27], v[152:153]
	v_pk_fma_f32 v[154:155], v[18:19], v[18:19], v[154:155]
	v_pk_fma_f32 v[152:153], v[28:29], v[28:29], v[152:153]
	v_pk_fma_f32 v[154:155], v[20:21], v[20:21], v[154:155]
	v_add_u32_e32 v150, 0x50000, v143
	v_cvt_pk_bf16_f32 v146, v30, v31
	v_cvt_pk_bf16_f32 v147, v32, v33
	v_cvt_pk_bf16_f32 v148, v26, v27
	v_cvt_pk_bf16_f32 v149, v28, v29
	global_store_dwordx4 v150, v[146:149], s[8:9]
	v_pk_add_f32 v[152:153], v[152:153], v[154:155]
	v_cvt_pk_bf16_f32 v168, v22, v23
	v_cvt_pk_bf16_f32 v169, v24, v25
	v_cvt_pk_bf16_f32 v170, v18, v19
	v_cvt_pk_bf16_f32 v171, v20, v21
	global_store_dwordx4 v150, v[168:171], s[8:9] offset:256
	v_add_f32_e32 v166, v152, v153
	v_pk_mul_f32 v[152:153], v[14:15], v[14:15]
	v_pk_mul_f32 v[154:155], v[6:7], v[6:7]
	v_pk_fma_f32 v[152:153], v[16:17], v[16:17], v[152:153]
	v_pk_fma_f32 v[154:155], v[8:9], v[8:9], v[154:155]
	v_pk_fma_f32 v[152:153], v[10:11], v[10:11], v[152:153]
	v_pk_fma_f32 v[154:155], v[2:3], v[2:3], v[154:155]
	v_pk_fma_f32 v[152:153], v[12:13], v[12:13], v[152:153]
	v_pk_fma_f32 v[154:155], v[4:5], v[4:5], v[154:155]
	v_add_u32_e32 v150, 0x58000, v143
	v_cvt_pk_bf16_f32 v146, v14, v15
	v_cvt_pk_bf16_f32 v147, v16, v17
	v_cvt_pk_bf16_f32 v148, v10, v11
	v_cvt_pk_bf16_f32 v149, v12, v13
	global_store_dwordx4 v150, v[146:149], s[8:9]
	v_pk_add_f32 v[152:153], v[152:153], v[154:155]
	v_cvt_pk_bf16_f32 v168, v6, v7
	v_cvt_pk_bf16_f32 v169, v8, v9
	v_cvt_pk_bf16_f32 v170, v2, v3
	v_cvt_pk_bf16_f32 v171, v4, v5
	global_store_dwordx4 v150, v[168:171], s[8:9] offset:256
	v_add_f32_e32 v167, v152, v153
	s_nop 1
	v_permlane16_swap_b32_e32 v164, v165
	v_permlane16_swap_b32_e32 v166, v167
	s_nop 1
	v_add_f32_e32 v164, v164, v165
	v_add_f32_e32 v166, v166, v167
	s_nop 1
	v_permlane32_swap_b32_e32 v164, v166
	s_nop 1
	v_add_f32_e32 v164, v164, v166
	global_store_dword v156, v164, s[10:11]
	s_branch .LBB0_718

; #define PG8_STAGE(bufoff, gbase, voff) do { _Pragma("unroll") for (int _i = 0; _i < 2; ++_i) \
;         __builtin_amdgcn_global_load_lds((const __attribute__((address_space(1))) unsigned*)((const char*)(gbase) + (voff)[_i]), (LAS unsigned*)(lds + (bufoff) + ldsw + _i * 8192), 16, 0, 0); } while (0)
; #define PG8_LDA(dst, b, h) do { _Pragma("unroll") for (int m = 0; m < 4; ++m) _Pragma("unroll") for (int k = 0; k < 2; ++k) dst[m][k] = *(const LAS bf16x8*)(lds + PG8_SA(b, h) + aoff + m * 2048 + k * 1024); } while (0)
; #define PG8_LDB(dst, b, h) do { _Pragma("unroll") for (int n = 0; n < 2; ++n) _Pragma("unroll") for (int k = 0; k < 2; ++k) dst[n][k] = *(const LAS bf16x8*)(lds + PG8_SB(b, h) + boff + n * 2048 + k * 1024); } while (0)
; #define PG8_MMA(ai, bj, At, Bt) do { __builtin_amdgcn_s_setprio(1); _Pragma("unroll") for (int m = 0; m < 4; ++m) _Pragma("unroll") for (int n = 0; n < 2; ++n) _Pragma("unroll") for (int k = 0; k < 2; ++k) \
;         acc[ai][bj][m][n] = __builtin_amdgcn_mfma_f32_16x16x32_bf16(Bt[n][k], At[m][k], acc[ai][bj][m][n], 0, 0, 0); __builtin_amdgcn_s_setprio(0); } while (0)
; #define PG8_WAIT_L(n) asm volatile("s_waitcnt lgkmcnt(" #n ")" ::: "memory")
; #define PG8_BAR __builtin_amdgcn_s_barrier()
; #define PG8_SCHED __builtin_amdgcn_sched_barrier(0)
; template <class Epi>
; __device__ __forceinline__ void gemm_phase(LAS unsigned char* lds, const Gemm g, const StaticOrder& S_in, const Epi& E, int sw) {
;     ...
;             const char* a1 = cA + (size_t)(t + 1) * kstep;
;             const char* a2 = last ? nA : cA + (size_t)(t + 2) * kstep; const char* b2 = last ? nB : cB + (size_t)(t + 2) * kstep;
;             const char* a3 = a2 + kstep; const char* b3 = b2 + kstep;
;             PG8_LDB(B0, 0, 0); PG8_SCHED; PG8_LDA(At, 0, 0); PG8_STAGE(PG8_SA(1, 1), a1 + hstepA, voffA);
;             PG8_WAIT_L(8); PG8_BAR; PG8_WAIT_L(0); PG8_MMA(0, 0, At, B0); PG8_BAR; PG8_SCHED;
;             PG8_LDB(B1, 0, 1); PG8_STAGE(PG8_SB(0, 0), b2, voffB);
;             PG8_BAR; PG8_WAIT_L(0); PG8_MMA(0, 1, At, B1); PG8_BAR;
;             PG8_LDA(At, 0, 1); PG8_STAGE(PG8_SA(0, 0), a2, voffA);
;             PG8_BAR; PG8_WAIT_L(0); PG8_MMA(1, 0, At, B0); PG8_BAR; PG8_SCHED;
.LBB0_1078:
	s_add_u32 s22, s20, 0xfff80080
	s_addc_u32 s23, s21, -1
	s_add_i32 s52, 0, 0x10000
	v_add_u32_e32 v154, s52, v144
	ds_read_b128 v[140:143], v154
	ds_read_b128 v[146:149], v154 offset:1024
	ds_read_b128 v[150:153], v154 offset:2048
	ds_read_b128 v[154:157], v154 offset:3072
	s_cmp_eq_u32 s51, 28
	s_cselect_b32 s25, s15, s23
	s_cselect_b32 s24, s47, s22
	s_cselect_b32 s23, s13, s50
	s_cselect_b32 s22, s48, s49
	v_lshl_add_u64 v[192:193], s[20:21], 0, v[136:137]
	s_add_i32 m0, s39, 0xc000
	ds_read_b128 v[158:161], v145
	ds_read_b128 v[162:165], v145 offset:1024
	ds_read_b128 v[166:169], v145 offset:2048
	ds_read_b128 v[172:175], v145 offset:3072
	ds_read_b128 v[176:179], v145 offset:4096
	ds_read_b128 v[180:183], v145 offset:5120
	ds_read_b128 v[184:187], v145 offset:6144
	ds_read_b128 v[188:191], v145 offset:7168
	global_load_lds_dwordx4 v[192:193], off
	v_lshl_add_u64 v[192:193], s[20:21], 0, v[138:139]
	s_add_i32 m0, s39, 0xe000
	s_nop 0
	global_load_lds_dwordx4 v[192:193], off
	s_waitcnt lgkmcnt(8)
	s_barrier
	s_waitcnt lgkmcnt(0)
	s_setprio 1
	s_waitcnt lgkmcnt(0)
	v_mfma_f32_16x16x32_bf16 v[126:129], v[140:143], v[158:161], v[126:129]
	v_mfma_f32_16x16x32_bf16 v[122:125], v[150:153], v[158:161], v[122:125]
	v_mfma_f32_16x16x32_bf16 v[110:113], v[140:143], v[166:169], v[110:113]
	v_mfma_f32_16x16x32_bf16 v[106:109], v[150:153], v[166:169], v[106:109]
	v_mfma_f32_16x16x32_bf16 v[94:97], v[140:143], v[176:179], v[94:97]
	v_mfma_f32_16x16x32_bf16 v[90:93], v[150:153], v[176:179], v[90:93]
	v_mfma_f32_16x16x32_bf16 v[78:81], v[140:143], v[184:187], v[78:81]
	v_mfma_f32_16x16x32_bf16 v[74:77], v[150:153], v[184:187], v[74:77]
	v_mfma_f32_16x16x32_bf16 v[126:129], v[146:149], v[162:165], v[126:129]
	v_mfma_f32_16x16x32_bf16 v[122:125], v[154:157], v[162:165], v[122:125]
	v_mfma_f32_16x16x32_bf16 v[110:113], v[146:149], v[172:175], v[110:113]
	v_mfma_f32_16x16x32_bf16 v[106:109], v[154:157], v[172:175], v[106:109]
	v_mfma_f32_16x16x32_bf16 v[94:97], v[146:149], v[180:183], v[94:97]
	v_mfma_f32_16x16x32_bf16 v[90:93], v[154:157], v[180:183], v[90:93]
	v_mfma_f32_16x16x32_bf16 v[78:81], v[146:149], v[188:191], v[78:81]
	v_mfma_f32_16x16x32_bf16 v[74:77], v[154:157], v[188:191], v[74:77]
	s_setprio 0
	s_barrier
	s_add_i32 s54, 0, 0x14000
	s_add_i32 s52, s52, s36
	v_add_u32_e32 v171, s54, v144
	v_lshl_add_u64 v[208:209], s[22:23], 0, v[0:1]
	s_mov_b32 m0, s52
	ds_read_b128 v[192:195], v171
	ds_read_b128 v[196:199], v171 offset:1024
	ds_read_b128 v[200:203], v171 offset:2048
	ds_read_b128 v[204:207], v171 offset:3072
	global_load_lds_dwordx4 v[208:209], off
	v_lshl_add_u64 v[210:211], s[22:23], 0, v[130:131]
	s_add_i32 m0, s52, 0x2000
	s_nop 0
	global_load_lds_dwordx4 v[210:211], off
	s_barrier
	s_waitcnt lgkmcnt(0)
	s_setprio 1
	s_waitcnt lgkmcnt(0)
	v_mfma_f32_16x16x32_bf16 v[118:121], v[192:195], v[158:161], v[118:121]
	v_mfma_f32_16x16x32_bf16 v[114:117], v[200:203], v[158:161], v[114:117]
	v_mfma_f32_16x16x32_bf16 v[102:105], v[192:195], v[166:169], v[102:105]
	v_mfma_f32_16x16x32_bf16 v[98:101], v[200:203], v[166:169], v[98:101]
	v_mfma_f32_16x16x32_bf16 v[86:89], v[192:195], v[176:179], v[86:89]
	v_mfma_f32_16x16x32_bf16 v[82:85], v[200:203], v[176:179], v[82:85]
	v_mfma_f32_16x16x32_bf16 v[70:73], v[192:195], v[184:187], v[70:73]
	v_mfma_f32_16x16x32_bf16 v[66:69], v[200:203], v[184:187], v[66:69]
	v_mfma_f32_16x16x32_bf16 v[118:121], v[196:199], v[162:165], v[118:121]
	v_mfma_f32_16x16x32_bf16 v[114:117], v[204:207], v[162:165], v[114:117]
	v_mfma_f32_16x16x32_bf16 v[102:105], v[196:199], v[172:175], v[102:105]
	v_mfma_f32_16x16x32_bf16 v[98:101], v[204:207], v[172:175], v[98:101]
	v_mfma_f32_16x16x32_bf16 v[86:89], v[196:199], v[180:183], v[86:89]
	v_mfma_f32_16x16x32_bf16 v[82:85], v[204:207], v[180:183], v[82:85]
	v_mfma_f32_16x16x32_bf16 v[70:73], v[196:199], v[188:191], v[70:73]
	v_mfma_f32_16x16x32_bf16 v[66:69], v[204:207], v[188:191], v[66:69]
	s_setprio 0
	s_mov_b32 m0, s39
	v_lshl_add_u64 v[212:213], s[24:25], 0, v[134:135]
	s_barrier
	ds_read_b128 v[158:161], v145 offset:16384
	ds_read_b128 v[162:165], v145 offset:17408
	ds_read_b128 v[166:169], v145 offset:18432
	ds_read_b128 v[172:175], v145 offset:19456
	ds_read_b128 v[176:179], v145 offset:20480
	ds_read_b128 v[180:183], v145 offset:21504
	ds_read_b128 v[184:187], v145 offset:22528
	ds_read_b128 v[188:191], v145 offset:23552
	global_load_lds_dwordx4 v[212:213], off
	v_lshl_add_u64 v[214:215], s[24:25], 0, v[132:133]
	s_mov_b32 m0, s40
	s_nop 0
	global_load_lds_dwordx4 v[214:215], off
	s_barrier
	s_waitcnt lgkmcnt(0)
	s_setprio 1
	s_waitcnt lgkmcnt(0)
	v_mfma_f32_16x16x32_bf16 v[62:65], v[140:143], v[158:161], v[62:65]
	v_mfma_f32_16x16x32_bf16 v[58:61], v[150:153], v[158:161], v[58:61]
	v_mfma_f32_16x16x32_bf16 v[46:49], v[140:143], v[166:169], v[46:49]
	v_mfma_f32_16x16x32_bf16 v[42:45], v[150:153], v[166:169], v[42:45]
	v_mfma_f32_16x16x32_bf16 v[30:33], v[140:143], v[176:179], v[30:33]
	v_mfma_f32_16x16x32_bf16 v[26:29], v[150:153], v[176:179], v[26:29]
	v_mfma_f32_16x16x32_bf16 v[14:17], v[140:143], v[184:187], v[14:17]
	v_mfma_f32_16x16x32_bf16 v[10:13], v[150:153], v[184:187], v[10:13]
	v_mfma_f32_16x16x32_bf16 v[62:65], v[146:149], v[162:165], v[62:65]
	v_mfma_f32_16x16x32_bf16 v[58:61], v[154:157], v[162:165], v[58:61]
	v_mfma_f32_16x16x32_bf16 v[46:49], v[146:149], v[172:175], v[46:49]
	v_mfma_f32_16x16x32_bf16 v[42:45], v[154:157], v[172:175], v[42:45]
	v_mfma_f32_16x16x32_bf16 v[30:33], v[146:149], v[180:183], v[30:33]
	v_mfma_f32_16x16x32_bf16 v[26:29], v[154:157], v[180:183], v[26:29]
	v_mfma_f32_16x16x32_bf16 v[14:17], v[146:149], v[188:191], v[14:17]
	v_mfma_f32_16x16x32_bf16 v[10:13], v[154:157], v[188:191], v[10:13]
	s_setprio 0
	s_barrier
; #define PG8_STAGE(bufoff, gbase, voff) do { _Pragma("unroll") for (int _i = 0; _i < 2; ++_i) \
;         __builtin_amdgcn_global_load_lds((const __attribute__((address_space(1))) unsigned*)((const char*)(gbase) + (voff)[_i]), (LAS unsigned*)(lds + (bufoff) + ldsw + _i * 8192), 16, 0, 0); } while (0)
; #define PG8_LDA(dst, b, h) do { _Pragma("unroll") for (int m = 0; m < 4; ++m) _Pragma("unroll") for (int k = 0; k < 2; ++k) dst[m][k] = *(const LAS bf16x8*)(lds + PG8_SA(b, h) + aoff + m * 2048 + k * 1024); } while (0)
; #define PG8_LDB(dst, b, h) do { _Pragma("unroll") for (int n = 0; n < 2; ++n) _Pragma("unroll") for (int k = 0; k < 2; ++k) dst[n][k] = *(const LAS bf16x8*)(lds + PG8_SB(b, h) + boff + n * 2048 + k * 1024); } while (0)
; #define PG8_MMA(ai, bj, At, Bt) do { __builtin_amdgcn_s_setprio(1); _Pragma("unroll") for (int m = 0; m < 4; ++m) _Pragma("unroll") for (int n = 0; n < 2; ++n) _Pragma("unroll") for (int k = 0; k < 2; ++k) \
;         acc[ai][bj][m][n] = __builtin_amdgcn_mfma_f32_16x16x32_bf16(Bt[n][k], At[m][k], acc[ai][bj][m][n], 0, 0, 0); __builtin_amdgcn_s_setprio(0); } while (0)
; #define PG8_WAIT_V(n) asm volatile("s_waitcnt vmcnt(" #n ")" ::: "memory")
; #define PG8_WAIT_L(n) asm volatile("s_waitcnt lgkmcnt(" #n ")" ::: "memory")
; #define PG8_BAR __builtin_amdgcn_s_barrier()
; #define PG8_SCHED __builtin_amdgcn_sched_barrier(0)
; template <class Epi>
; __device__ __forceinline__ void gemm_phase(LAS unsigned char* lds, const Gemm g, const StaticOrder& S_in, const Epi& E, int sw) {
;     ...
;             PG8_STAGE(PG8_SB(0, 1), b2 + hstepB, voffB);
;             PG8_WAIT_V(6); PG8_BAR; PG8_MMA(1, 1, At, B1); PG8_BAR;
;             PG8_LDB(B0, 1, 0); PG8_SCHED; PG8_LDA(At, 1, 0); PG8_STAGE(PG8_SA(0, 1), a2 + hstepA, voffA);
;             PG8_WAIT_L(8); PG8_BAR; PG8_WAIT_L(0); PG8_MMA(0, 0, At, B0); PG8_BAR; PG8_SCHED;
;             PG8_LDB(B1, 1, 1); PG8_STAGE(PG8_SB(1, 0), b3, voffB);
;             PG8_BAR; PG8_WAIT_L(0); PG8_MMA(0, 1, At, B1); PG8_BAR;
;             PG8_LDA(At, 1, 1); PG8_STAGE(PG8_SA(1, 0), a3, voffA);
;             PG8_BAR; PG8_WAIT_L(0); PG8_MMA(1, 0, At, B0); PG8_BAR; PG8_SCHED;
	s_add_u32 s52, s22, 0x80000
	s_addc_u32 s53, s23, 0
	s_add_i32 s54, s54, s36
	v_lshl_add_u64 v[140:141], s[52:53], 0, v[0:1]
	s_mov_b32 m0, s54
	s_nop 0
	global_load_lds_dwordx4 v[140:141], off
	v_lshl_add_u64 v[140:141], s[52:53], 0, v[130:131]
	s_add_i32 m0, s54, 0x2000
	s_nop 0
	global_load_lds_dwordx4 v[140:141], off
	s_waitcnt vmcnt(6)
	s_barrier
	s_setprio 1
	v_mfma_f32_16x16x32_bf16 v[54:57], v[192:195], v[158:161], v[54:57]
	v_mfma_f32_16x16x32_bf16 v[50:53], v[200:203], v[158:161], v[50:53]
	v_mfma_f32_16x16x32_bf16 v[38:41], v[192:195], v[166:169], v[38:41]
	v_mfma_f32_16x16x32_bf16 v[34:37], v[200:203], v[166:169], v[34:37]
	v_mfma_f32_16x16x32_bf16 v[22:25], v[192:195], v[176:179], v[22:25]
	v_mfma_f32_16x16x32_bf16 v[18:21], v[200:203], v[176:179], v[18:21]
	v_mfma_f32_16x16x32_bf16 v[6:9], v[192:195], v[184:187], v[6:9]
	v_mfma_f32_16x16x32_bf16 v[2:5], v[200:203], v[184:187], v[2:5]
	v_mfma_f32_16x16x32_bf16 v[54:57], v[196:199], v[162:165], v[54:57]
	v_mfma_f32_16x16x32_bf16 v[50:53], v[204:207], v[162:165], v[50:53]
	v_mfma_f32_16x16x32_bf16 v[38:41], v[196:199], v[172:175], v[38:41]
	v_mfma_f32_16x16x32_bf16 v[34:37], v[204:207], v[172:175], v[34:37]
	v_mfma_f32_16x16x32_bf16 v[22:25], v[196:199], v[180:183], v[22:25]
	v_mfma_f32_16x16x32_bf16 v[18:21], v[204:207], v[180:183], v[18:21]
	v_mfma_f32_16x16x32_bf16 v[6:9], v[196:199], v[188:191], v[6:9]
	v_mfma_f32_16x16x32_bf16 v[2:5], v[204:207], v[188:191], v[2:5]
	s_setprio 0
	s_add_i32 s52, 0, 0x18000
	v_add_u32_e32 v154, s52, v144
	s_barrier
	ds_read_b128 v[140:143], v154
	ds_read_b128 v[146:149], v154 offset:1024
	ds_read_b128 v[150:153], v154 offset:2048
	ds_read_b128 v[154:157], v154 offset:3072
	s_add_u32 s24, s24, 0x80000
	s_addc_u32 s25, s25, 0
	s_mov_b32 m0, s41
	v_lshl_add_u64 v[192:193], s[24:25], 0, v[134:135]
	ds_read_b128 v[158:161], v145 offset:32768
	ds_read_b128 v[162:165], v145 offset:33792
	ds_read_b128 v[166:169], v145 offset:34816
	ds_read_b128 v[172:175], v145 offset:35840
	ds_read_b128 v[176:179], v145 offset:36864
	ds_read_b128 v[180:183], v145 offset:37888
	ds_read_b128 v[184:187], v145 offset:38912
	ds_read_b128 v[188:191], v145 offset:39936
	global_load_lds_dwordx4 v[192:193], off
	v_lshl_add_u64 v[192:193], s[24:25], 0, v[132:133]
	s_mov_b32 m0, s42
	s_nop 0
	global_load_lds_dwordx4 v[192:193], off
	s_waitcnt lgkmcnt(8)
	s_barrier
	s_waitcnt lgkmcnt(0)
	s_setprio 1
	s_waitcnt lgkmcnt(0)
	v_mfma_f32_16x16x32_bf16 v[126:129], v[140:143], v[158:161], v[126:129]
	v_mfma_f32_16x16x32_bf16 v[122:125], v[150:153], v[158:161], v[122:125]
	v_mfma_f32_16x16x32_bf16 v[110:113], v[140:143], v[166:169], v[110:113]
	v_mfma_f32_16x16x32_bf16 v[106:109], v[150:153], v[166:169], v[106:109]
	v_mfma_f32_16x16x32_bf16 v[94:97], v[140:143], v[176:179], v[94:97]
	v_mfma_f32_16x16x32_bf16 v[90:93], v[150:153], v[176:179], v[90:93]
	v_mfma_f32_16x16x32_bf16 v[78:81], v[140:143], v[184:187], v[78:81]
	v_mfma_f32_16x16x32_bf16 v[74:77], v[150:153], v[184:187], v[74:77]
	v_mfma_f32_16x16x32_bf16 v[126:129], v[146:149], v[162:165], v[126:129]
	v_mfma_f32_16x16x32_bf16 v[122:125], v[154:157], v[162:165], v[122:125]
	v_mfma_f32_16x16x32_bf16 v[110:113], v[146:149], v[172:175], v[110:113]
	v_mfma_f32_16x16x32_bf16 v[106:109], v[154:157], v[172:175], v[106:109]
	v_mfma_f32_16x16x32_bf16 v[94:97], v[146:149], v[180:183], v[94:97]
	v_mfma_f32_16x16x32_bf16 v[90:93], v[154:157], v[180:183], v[90:93]
	v_mfma_f32_16x16x32_bf16 v[78:81], v[146:149], v[188:191], v[78:81]
	v_mfma_f32_16x16x32_bf16 v[74:77], v[154:157], v[188:191], v[74:77]
	s_setprio 0
	s_barrier
	s_add_i32 s24, 0, 0x1c000
	s_add_i32 s25, s52, s36
	v_add_u32_e32 v171, s24, v144
	v_lshl_add_u64 v[208:209], v[208:209], 0, s[86:87]
	s_mov_b32 m0, s25
	ds_read_b128 v[192:195], v171
	ds_read_b128 v[196:199], v171 offset:1024
	ds_read_b128 v[200:203], v171 offset:2048
	ds_read_b128 v[204:207], v171 offset:3072
	global_load_lds_dwordx4 v[208:209], off
	v_lshl_add_u64 v[208:209], v[210:211], 0, s[86:87]
	s_add_i32 m0, s25, 0x2000
	s_nop 0
	global_load_lds_dwordx4 v[208:209], off
	s_barrier
	s_waitcnt lgkmcnt(0)
	s_setprio 1
	s_waitcnt lgkmcnt(0)
	v_mfma_f32_16x16x32_bf16 v[118:121], v[192:195], v[158:161], v[118:121]
	v_mfma_f32_16x16x32_bf16 v[114:117], v[200:203], v[158:161], v[114:117]
	v_mfma_f32_16x16x32_bf16 v[102:105], v[192:195], v[166:169], v[102:105]
	v_mfma_f32_16x16x32_bf16 v[98:101], v[200:203], v[166:169], v[98:101]
	v_mfma_f32_16x16x32_bf16 v[86:89], v[192:195], v[176:179], v[86:89]
	v_mfma_f32_16x16x32_bf16 v[82:85], v[200:203], v[176:179], v[82:85]
	v_mfma_f32_16x16x32_bf16 v[70:73], v[192:195], v[184:187], v[70:73]
	v_mfma_f32_16x16x32_bf16 v[66:69], v[200:203], v[184:187], v[66:69]
	v_mfma_f32_16x16x32_bf16 v[118:121], v[196:199], v[162:165], v[118:121]
	v_mfma_f32_16x16x32_bf16 v[114:117], v[204:207], v[162:165], v[114:117]
	v_mfma_f32_16x16x32_bf16 v[102:105], v[196:199], v[172:175], v[102:105]
	v_mfma_f32_16x16x32_bf16 v[98:101], v[204:207], v[172:175], v[98:101]
	v_mfma_f32_16x16x32_bf16 v[86:89], v[196:199], v[180:183], v[86:89]
	v_mfma_f32_16x16x32_bf16 v[82:85], v[204:207], v[180:183], v[82:85]
	v_mfma_f32_16x16x32_bf16 v[70:73], v[196:199], v[188:191], v[70:73]
	v_mfma_f32_16x16x32_bf16 v[66:69], v[204:207], v[188:191], v[66:69]
	s_setprio 0
	s_mov_b32 m0, s43
	v_lshl_add_u64 v[208:209], v[212:213], 0, s[86:87]
	s_barrier
	ds_read_b128 v[158:161], v145 offset:49152
	ds_read_b128 v[162:165], v145 offset:50176
	ds_read_b128 v[166:169], v145 offset:51200
	ds_read_b128 v[172:175], v145 offset:52224
	ds_read_b128 v[176:179], v145 offset:53248
	ds_read_b128 v[180:183], v145 offset:54272
	ds_read_b128 v[184:187], v145 offset:55296
	ds_read_b128 v[188:191], v145 offset:56320
	global_load_lds_dwordx4 v[208:209], off
	v_lshl_add_u64 v[208:209], v[214:215], 0, s[86:87]
	s_mov_b32 m0, s44
	s_nop 0
	global_load_lds_dwordx4 v[208:209], off
	s_barrier
; __device__ __forceinline__ unsigned cvt_pk_bf16(float lo, float hi) { unsigned r; asm volatile("v_cvt_pk_bf16_f32 %0, %1, %2" : "=v"(r) : "v"(lo), "v"(hi)); return r; }
; __device__ __forceinline__ int ltid(int sw) { unsigned z = 0u; asm volatile("" : "+s"(sw), "+s"(z)); int t = sw * 64 + (int)__builtin_amdgcn_mbcnt_hi(~0u, __builtin_amdgcn_mbcnt_lo(~0u, z)); asm volatile("" : "+v"(t)); return t; }
; #define PG8_STAGE(bufoff, gbase, voff) do { _Pragma("unroll") for (int _i = 0; _i < 2; ++_i) \
;         __builtin_amdgcn_global_load_lds((const __attribute__((address_space(1))) unsigned*)((const char*)(gbase) + (voff)[_i]), (LAS unsigned*)(lds + (bufoff) + ldsw + _i * 8192), 16, 0, 0); } while (0)
; #define PG8_WAIT_V(n) asm volatile("s_waitcnt vmcnt(" #n ")" ::: "memory")
; #define PG8_WAIT_L(n) asm volatile("s_waitcnt lgkmcnt(" #n ")" ::: "memory")
; #define PG8_BAR __builtin_amdgcn_s_barrier()
; #define PG8_SCHED __builtin_amdgcn_sched_barrier(0)
; template <class Epi>
; __device__ __forceinline__ void gemm_phase(LAS unsigned char* lds, const Gemm g, const StaticOrder& S_in, const Epi& E, int sw) {
;     ...
;             PG8_BAR; PG8_WAIT_L(0); PG8_MMA(1, 0, At, B0); PG8_BAR; PG8_SCHED;
;             PG8_STAGE(PG8_SB(1, 1), b3 + hstepB, voffB);
;             PG8_WAIT_V(6); PG8_BAR; PG8_MMA(1, 1, At, B1); PG8_BAR;
;         }
;     EPI_ZERO_INIT
;     __device__ __forceinline__ void operator()(AccRef acc, const Unit& u, int sw) const {
;         const int tid_ = ltid(sw), lane_ = tid_ & 63, wr = sw >> 2, wc = sw & 3, fr = lane_ & 15, fq = lane_ >> 4;
;         const int row0 = u.pm * BM + wr * 64 + fr, col0 = u.pn * BM + wc * 32 + 8 * fq;
; #pragma unroll
;         for (int ai = 0; ai < 2; ++ai)
; #pragma unroll
;             for (int m = 0; m < 4; ++m) { const int row = row0 + ai * HALF + m * 16; bf16_t* rowp = O + (size_t)row * D + col0; float s = 0.f;
; #pragma unroll
;                 for (int bj = 0; bj < 2; ++bj) { const f32x4 v0 = acc[ai][bj][m][0], v1 = acc[ai][bj][m][1];
;                     s += (v0[0] * v0[0] + v0[1] * v0[1]) + (v0[2] * v0[2] + v0[3] * v0[3]) + (v1[0] * v1[0] + v1[1] * v1[1]) + (v1[2] * v1[2] + v1[3] * v1[3]);
;                     u32x4 w; w.x = cvt_pk_bf16(v0[0], v0[1]); w.y = cvt_pk_bf16(v0[2], v0[3]); w.z = cvt_pk_bf16(v1[0], v1[1]); w.w = cvt_pk_bf16(v1[2], v1[3]);
;                     *(u32x4*)(rowp + bj * HALF) = w; }
	s_waitcnt lgkmcnt(0)
	s_setprio 1
	s_waitcnt lgkmcnt(0)
	v_mfma_f32_16x16x32_bf16 v[62:65], v[140:143], v[158:161], v[62:65]
	v_mfma_f32_16x16x32_bf16 v[58:61], v[150:153], v[158:161], v[58:61]
	v_mfma_f32_16x16x32_bf16 v[46:49], v[140:143], v[166:169], v[46:49]
	v_mfma_f32_16x16x32_bf16 v[42:45], v[150:153], v[166:169], v[42:45]
	v_mfma_f32_16x16x32_bf16 v[30:33], v[140:143], v[176:179], v[30:33]
	v_mfma_f32_16x16x32_bf16 v[26:29], v[150:153], v[176:179], v[26:29]
	v_mfma_f32_16x16x32_bf16 v[14:17], v[140:143], v[184:187], v[14:17]
	v_mfma_f32_16x16x32_bf16 v[10:13], v[150:153], v[184:187], v[10:13]
	v_mfma_f32_16x16x32_bf16 v[62:65], v[146:149], v[162:165], v[62:65]
	v_mfma_f32_16x16x32_bf16 v[58:61], v[154:157], v[162:165], v[58:61]
	v_mfma_f32_16x16x32_bf16 v[46:49], v[146:149], v[172:175], v[46:49]
	v_mfma_f32_16x16x32_bf16 v[42:45], v[154:157], v[172:175], v[42:45]
	v_mfma_f32_16x16x32_bf16 v[30:33], v[146:149], v[180:183], v[30:33]
	v_mfma_f32_16x16x32_bf16 v[26:29], v[154:157], v[180:183], v[26:29]
	v_mfma_f32_16x16x32_bf16 v[14:17], v[146:149], v[188:191], v[14:17]
	v_mfma_f32_16x16x32_bf16 v[10:13], v[154:157], v[188:191], v[10:13]
	s_setprio 0
	s_barrier
	s_add_u32 s22, s22, 0x80080
	s_addc_u32 s23, s23, 0
	s_add_i32 s24, s24, s36
	v_lshl_add_u64 v[140:141], s[22:23], 0, v[0:1]
	s_mov_b32 m0, s24
	s_nop 0
	global_load_lds_dwordx4 v[140:141], off
	v_lshl_add_u64 v[140:141], s[22:23], 0, v[130:131]
	s_add_i32 m0, s24, 0x2000
	s_nop 0
	global_load_lds_dwordx4 v[140:141], off
	s_waitcnt vmcnt(6)
	s_barrier
	s_setprio 1
	v_mfma_f32_16x16x32_bf16 v[54:57], v[192:195], v[158:161], v[54:57]
	v_mfma_f32_16x16x32_bf16 v[50:53], v[200:203], v[158:161], v[50:53]
	v_mfma_f32_16x16x32_bf16 v[38:41], v[192:195], v[166:169], v[38:41]
	v_mfma_f32_16x16x32_bf16 v[34:37], v[200:203], v[166:169], v[34:37]
	v_mfma_f32_16x16x32_bf16 v[22:25], v[192:195], v[176:179], v[22:25]
	v_mfma_f32_16x16x32_bf16 v[18:21], v[200:203], v[176:179], v[18:21]
	v_mfma_f32_16x16x32_bf16 v[6:9], v[192:195], v[184:187], v[6:9]
	v_mfma_f32_16x16x32_bf16 v[2:5], v[200:203], v[184:187], v[2:5]
	v_mfma_f32_16x16x32_bf16 v[54:57], v[196:199], v[162:165], v[54:57]
	v_mfma_f32_16x16x32_bf16 v[50:53], v[204:207], v[162:165], v[50:53]
	v_mfma_f32_16x16x32_bf16 v[38:41], v[196:199], v[172:175], v[38:41]
	v_mfma_f32_16x16x32_bf16 v[34:37], v[204:207], v[172:175], v[34:37]
	v_mfma_f32_16x16x32_bf16 v[22:25], v[196:199], v[180:183], v[22:25]
	v_mfma_f32_16x16x32_bf16 v[18:21], v[204:207], v[180:183], v[18:21]
	v_mfma_f32_16x16x32_bf16 v[6:9], v[196:199], v[188:191], v[6:9]
	v_mfma_f32_16x16x32_bf16 v[2:5], v[204:207], v[188:191], v[2:5]
	s_setprio 0
	s_add_i32 s51, s51, 2
	s_add_u32 s20, s20, 0x100
	s_addc_u32 s21, s21, 0
	s_add_u32 s49, s49, 0x100
	s_addc_u32 s50, s50, 0
	s_cmp_gt_u32 s51, 29
	s_barrier
	s_cbranch_scc0 .LBB0_1078
	v_mbcnt_lo_u32_b32 v140, -1, 0
	v_mbcnt_hi_u32_b32 v140, -1, v140
	s_lshl_b32 s6, s6, 8
	s_add_i32 s6, s6, s3
	v_readlane_b32 s13, v255, 5
	v_and_b32_e32 v141, 15, v140
	v_lshrrev_b32_e32 v142, 4, v140
	v_or_b32_e32 v141, s6, v141
	v_lshl_add_u32 v151, v142, 4, v141
	v_lshlrev_b32_e32 v142, 3, v142
	s_lshl_b32 s6, s7, 8
	s_or_b32 s6, s6, s13
	v_readlane_b32 s13, v255, 4
	v_or_b32_e32 v142, s6, v142
	v_lshlrev_b32_e32 v143, 11, v141
	v_lshl_add_u32 v143, v142, 1, v143
	s_lshl_b32 s7, s7, 2
	s_add_i32 s7, s7, s13
	s_lshl_b32 s7, s7, 2
	v_lshlrev_b32_e32 v151, 6, v151
	v_add_u32_e32 v151, s7, v151
	v_add_u32_e32 v156, 0x2000, v151
	v_pk_mul_f32 v[152:153], v[126:127], v[126:127]
	v_pk_mul_f32 v[154:155], v[118:119], v[118:119]
	v_pk_fma_f32 v[152:153], v[128:129], v[128:129], v[152:153]
	v_pk_fma_f32 v[154:155], v[120:121], v[120:121], v[154:155]
	v_pk_fma_f32 v[152:153], v[122:123], v[122:123], v[152:153]
	v_pk_fma_f32 v[154:155], v[114:115], v[114:115], v[154:155]
	v_pk_fma_f32 v[152:153], v[124:125], v[124:125], v[152:153]
	v_pk_fma_f32 v[154:155], v[116:117], v[116:117], v[154:155]
	v_cvt_pk_bf16_f32 v146, v126, v127
	v_cvt_pk_bf16_f32 v147, v128, v129
	v_cvt_pk_bf16_f32 v148, v122, v123
	v_cvt_pk_bf16_f32 v149, v124, v125
	global_store_dwordx4 v143, v[146:149], s[8:9]
	v_pk_add_f32 v[152:153], v[152:153], v[154:155]
	v_cvt_pk_bf16_f32 v168, v118, v119
	v_cvt_pk_bf16_f32 v169, v120, v121
	v_cvt_pk_bf16_f32 v170, v114, v115
	v_cvt_pk_bf16_f32 v171, v116, v117
	global_store_dwordx4 v143, v[168:171], s[8:9] offset:256
	v_add_f32_e32 v160, v152, v153
	v_pk_mul_f32 v[152:153], v[110:111], v[110:111]
	v_pk_mul_f32 v[154:155], v[102:103], v[102:103]
	v_pk_fma_f32 v[152:153], v[112:113], v[112:113], v[152:153]
	v_pk_fma_f32 v[154:155], v[104:105], v[104:105], v[154:155]
	v_pk_fma_f32 v[152:153], v[106:107], v[106:107], v[152:153]
	v_pk_fma_f32 v[154:155], v[98:99], v[98:99], v[154:155]
	v_pk_fma_f32 v[152:153], v[108:109], v[108:109], v[152:153]
	v_pk_fma_f32 v[154:155], v[100:101], v[100:101], v[154:155]
	v_add_u32_e32 v150, 0x8000, v143
	v_cvt_pk_bf16_f32 v146, v110, v111
	v_cvt_pk_bf16_f32 v147, v112, v113
	v_cvt_pk_bf16_f32 v148, v106, v107
	v_cvt_pk_bf16_f32 v149, v108, v109
	global_store_dwordx4 v150, v[146:149], s[8:9]
	v_pk_add_f32 v[152:153], v[152:153], v[154:155]
	v_cvt_pk_bf16_f32 v168, v102, v103
	v_cvt_pk_bf16_f32 v169, v104, v105
	v_cvt_pk_bf16_f32 v170, v98, v99
	v_cvt_pk_bf16_f32 v171, v100, v101
	global_store_dwordx4 v150, v[168:171], s[8:9] offset:256
	v_add_f32_e32 v161, v152, v153
	v_pk_mul_f32 v[152:153], v[94:95], v[94:95]
	v_pk_mul_f32 v[154:155], v[86:87], v[86:87]
	v_pk_fma_f32 v[152:153], v[96:97], v[96:97], v[152:153]
	v_pk_fma_f32 v[154:155], v[88:89], v[88:89], v[154:155]
	v_pk_fma_f32 v[152:153], v[90:91], v[90:91], v[152:153]
; __device__ __forceinline__ unsigned cvt_pk_bf16(float lo, float hi) { unsigned r; asm volatile("v_cvt_pk_bf16_f32 %0, %1, %2" : "=v"(r) : "v"(lo), "v"(hi)); return r; }
;     EPI_ZERO_INIT
;     __device__ __forceinline__ void operator()(AccRef acc, const Unit& u, int sw) const {
;     ...
;             for (int m = 0; m < 4; ++m) { const int row = row0 + ai * HALF + m * 16; bf16_t* rowp = O + (size_t)row * D + col0; float s = 0.f;
; #pragma unroll
;                 for (int bj = 0; bj < 2; ++bj) { const f32x4 v0 = acc[ai][bj][m][0], v1 = acc[ai][bj][m][1];
;                     s += (v0[0] * v0[0] + v0[1] * v0[1]) + (v0[2] * v0[2] + v0[3] * v0[3]) + (v1[0] * v1[0] + v1[1] * v1[1]) + (v1[2] * v1[2] + v1[3] * v1[3]);
;                     u32x4 w; w.x = cvt_pk_bf16(v0[0], v0[1]); w.y = cvt_pk_bf16(v0[2], v0[3]); w.z = cvt_pk_bf16(v1[0], v1[1]); w.w = cvt_pk_bf16(v1[2], v1[3]);
;                     *(u32x4*)(rowp + bj * HALF) = w; }
;                 s += __shfl_xor(s, 16); s += __shfl_xor(s, 32);
;                 if (fq == 0) SSQ[(size_t)row * 16 + u.pn * 4 + wc] = s; }
	v_pk_fma_f32 v[154:155], v[82:83], v[82:83], v[154:155]
	v_pk_fma_f32 v[152:153], v[92:93], v[92:93], v[152:153]
	v_pk_fma_f32 v[154:155], v[84:85], v[84:85], v[154:155]
	v_add_u32_e32 v150, 0x10000, v143
	v_cvt_pk_bf16_f32 v146, v94, v95
	v_cvt_pk_bf16_f32 v147, v96, v97
	v_cvt_pk_bf16_f32 v148, v90, v91
	v_cvt_pk_bf16_f32 v149, v92, v93
	global_store_dwordx4 v150, v[146:149], s[8:9]
	v_pk_add_f32 v[152:153], v[152:153], v[154:155]
	v_cvt_pk_bf16_f32 v168, v86, v87
	v_cvt_pk_bf16_f32 v169, v88, v89
	v_cvt_pk_bf16_f32 v170, v82, v83
	v_cvt_pk_bf16_f32 v171, v84, v85
	global_store_dwordx4 v150, v[168:171], s[8:9] offset:256
	v_add_f32_e32 v162, v152, v153
	v_pk_mul_f32 v[152:153], v[78:79], v[78:79]
	v_pk_mul_f32 v[154:155], v[70:71], v[70:71]
	v_pk_fma_f32 v[152:153], v[80:81], v[80:81], v[152:153]
	v_pk_fma_f32 v[154:155], v[72:73], v[72:73], v[154:155]
	v_pk_fma_f32 v[152:153], v[74:75], v[74:75], v[152:153]
	v_pk_fma_f32 v[154:155], v[66:67], v[66:67], v[154:155]
	v_pk_fma_f32 v[152:153], v[76:77], v[76:77], v[152:153]
	v_pk_fma_f32 v[154:155], v[68:69], v[68:69], v[154:155]
	v_add_u32_e32 v150, 0x18000, v143
	v_cvt_pk_bf16_f32 v146, v78, v79
	v_cvt_pk_bf16_f32 v147, v80, v81
	v_cvt_pk_bf16_f32 v148, v74, v75
	v_cvt_pk_bf16_f32 v149, v76, v77
	global_store_dwordx4 v150, v[146:149], s[8:9]
	v_pk_add_f32 v[152:153], v[152:153], v[154:155]
	v_cvt_pk_bf16_f32 v168, v70, v71
	v_cvt_pk_bf16_f32 v169, v72, v73
	v_cvt_pk_bf16_f32 v170, v66, v67
	v_cvt_pk_bf16_f32 v171, v68, v69
	global_store_dwordx4 v150, v[168:171], s[8:9] offset:256
	v_add_f32_e32 v163, v152, v153
	s_nop 1
	v_permlane16_swap_b32_e32 v160, v161
	v_permlane16_swap_b32_e32 v162, v163
	s_nop 1
	v_add_f32_e32 v160, v160, v161
	v_add_f32_e32 v162, v162, v163
	s_nop 1
	v_permlane32_swap_b32_e32 v160, v162
	s_nop 1
	v_add_f32_e32 v160, v160, v162
	global_store_dword v151, v160, s[10:11]
	v_pk_mul_f32 v[152:153], v[62:63], v[62:63]
	v_pk_mul_f32 v[154:155], v[54:55], v[54:55]
	v_pk_fma_f32 v[152:153], v[64:65], v[64:65], v[152:153]
	v_pk_fma_f32 v[154:155], v[56:57], v[56:57], v[154:155]
	v_pk_fma_f32 v[152:153], v[58:59], v[58:59], v[152:153]
	v_pk_fma_f32 v[154:155], v[50:51], v[50:51], v[154:155]
	v_pk_fma_f32 v[152:153], v[60:61], v[60:61], v[152:153]
	v_pk_fma_f32 v[154:155], v[52:53], v[52:53], v[154:155]
	v_add_u32_e32 v150, 0x40000, v143
	v_cvt_pk_bf16_f32 v146, v62, v63
	v_cvt_pk_bf16_f32 v147, v64, v65
	v_cvt_pk_bf16_f32 v148, v58, v59
	v_cvt_pk_bf16_f32 v149, v60, v61
	global_store_dwordx4 v150, v[146:149], s[8:9]
	v_pk_add_f32 v[152:153], v[152:153], v[154:155]
	v_cvt_pk_bf16_f32 v168, v54, v55
	v_cvt_pk_bf16_f32 v169, v56, v57
	v_cvt_pk_bf16_f32 v170, v50, v51
	v_cvt_pk_bf16_f32 v171, v52, v53
	global_store_dwordx4 v150, v[168:171], s[8:9] offset:256
	v_add_f32_e32 v164, v152, v153
	v_pk_mul_f32 v[152:153], v[46:47], v[46:47]
	v_pk_mul_f32 v[154:155], v[38:39], v[38:39]
	v_pk_fma_f32 v[152:153], v[48:49], v[48:49], v[152:153]
	v_pk_fma_f32 v[154:155], v[40:41], v[40:41], v[154:155]
	v_pk_fma_f32 v[152:153], v[42:43], v[42:43], v[152:153]
	v_pk_fma_f32 v[154:155], v[34:35], v[34:35], v[154:155]
	v_pk_fma_f32 v[152:153], v[44:45], v[44:45], v[152:153]
	v_pk_fma_f32 v[154:155], v[36:37], v[36:37], v[154:155]
	v_add_u32_e32 v150, 0x48000, v143
	v_cvt_pk_bf16_f32 v146, v46, v47
	v_cvt_pk_bf16_f32 v147, v48, v49
	v_cvt_pk_bf16_f32 v148, v42, v43
	v_cvt_pk_bf16_f32 v149, v44, v45
	global_store_dwordx4 v150, v[146:149], s[8:9]
	v_pk_add_f32 v[152:153], v[152:153], v[154:155]
	v_cvt_pk_bf16_f32 v168, v38, v39
	v_cvt_pk_bf16_f32 v169, v40, v41
	v_cvt_pk_bf16_f32 v170, v34, v35
	v_cvt_pk_bf16_f32 v171, v36, v37
	global_store_dwordx4 v150, v[168:171], s[8:9] offset:256
	v_add_f32_e32 v165, v152, v153
	v_pk_mul_f32 v[152:153], v[30:31], v[30:31]
	v_pk_mul_f32 v[154:155], v[22:23], v[22:23]
	v_pk_fma_f32 v[152:153], v[32:33], v[32:33], v[152:153]
	v_pk_fma_f32 v[154:155], v[24:25], v[24:25], v[154:155]
	v_pk_fma_f32 v[152:153], v[26:27], v[26:27], v[152:153]
	v_pk_fma_f32 v[154:155], v[18:19], v[18:19], v[154:155]
	v_pk_fma_f32 v[152:153], v[28:29], v[28:29], v[152:153]
	v_pk_fma_f32 v[154:155], v[20:21], v[20:21], v[154:155]
	v_add_u32_e32 v150, 0x50000, v143
	v_cvt_pk_bf16_f32 v146, v30, v31
	v_cvt_pk_bf16_f32 v147, v32, v33
	v_cvt_pk_bf16_f32 v148, v26, v27
	v_cvt_pk_bf16_f32 v149, v28, v29
	global_store_dwordx4 v150, v[146:149], s[8:9]
	v_pk_add_f32 v[152:153], v[152:153], v[154:155]
	v_cvt_pk_bf16_f32 v168, v22, v23
	v_cvt_pk_bf16_f32 v169, v24, v25
	v_cvt_pk_bf16_f32 v170, v18, v19
	v_cvt_pk_bf16_f32 v171, v20, v21
	global_store_dwordx4 v150, v[168:171], s[8:9] offset:256
	v_add_f32_e32 v166, v152, v153
	v_pk_mul_f32 v[152:153], v[14:15], v[14:15]
	v_pk_mul_f32 v[154:155], v[6:7], v[6:7]
	v_pk_fma_f32 v[152:153], v[16:17], v[16:17], v[152:153]
	v_pk_fma_f32 v[154:155], v[8:9], v[8:9], v[154:155]
	v_pk_fma_f32 v[152:153], v[10:11], v[10:11], v[152:153]
	v_pk_fma_f32 v[154:155], v[2:3], v[2:3], v[154:155]
	v_pk_fma_f32 v[152:153], v[12:13], v[12:13], v[152:153]
	v_pk_fma_f32 v[154:155], v[4:5], v[4:5], v[154:155]
	v_add_u32_e32 v150, 0x58000, v143
	v_cvt_pk_bf16_f32 v146, v14, v15
	v_cvt_pk_bf16_f32 v147, v16, v17
	v_cvt_pk_bf16_f32 v148, v10, v11
	v_cvt_pk_bf16_f32 v149, v12, v13
	global_store_dwordx4 v150, v[146:149], s[8:9]
	v_pk_add_f32 v[152:153], v[152:153], v[154:155]
	v_cvt_pk_bf16_f32 v168, v6, v7
	v_cvt_pk_bf16_f32 v169, v8, v9
	v_cvt_pk_bf16_f32 v170, v2, v3
	v_cvt_pk_bf16_f32 v171, v4, v5
	global_store_dwordx4 v150, v[168:171], s[8:9] offset:256
	v_add_f32_e32 v167, v152, v153
	s_nop 1
	v_permlane16_swap_b32_e32 v164, v165
	v_permlane16_swap_b32_e32 v166, v167
	s_nop 1
	v_add_f32_e32 v164, v164, v165
	v_add_f32_e32 v166, v166, v167
	s_nop 1
	v_permlane32_swap_b32_e32 v164, v166
	s_nop 1
	v_add_f32_e32 v164, v164, v166
	global_store_dword v156, v164, s[10:11]
	s_branch .LBB0_1074
